# s5_scan: 8 LDS reads batched; hg<true>: step-4 MFMAs interleaved into step-5 VALU after barrier d, ST packing at chunk end
# speedup vs baseline: 1.0035x; 1.0029x over previous
; #define LAS __attribute__((address_space(3)))
; __device__ __forceinline__ void s5_scan(const Prm& P, LAS unsigned char* lds, int item, int wave) {
;     ...
;         for (int i = 0; i < 4; ++i) { const int idx = tid + i * 512, r = idx >> 4, part = (idx >> 3) & 1, c4 = idx & 7;
;             *(LAS f32x4*)(tile + r * 64 + part * 32 + c4 * 4) = *(const f32x4*)(E + (rowbase + r) * 128 + part * 64 + half * 32 + c4 * 4); }
;         __syncthreads();
;         const int r0 = ss * 8; float xr[8], xi[8]; float pr = 0.f, pi = 0.f;
; #pragma unroll
;         for (int j = 0; j < 8; ++j) { xr[j] = pr; xi[j] = pi; const float er = tile[(r0 + j) * 64 + nl], ei = tile[(r0 + j) * 64 + 32 + nl];
;             const float a = Lr * pr - Li * pi + er, c = Lr * pi + Li * pr + ei; pr = a; pi = c; }
;         agg[ss * 64 + nl] = pr; agg[ss * 64 + 32 + nl] = pi;
;         __syncthreads();
;         float cr = car, ci = cai, mr = 0.f, mi = 0.f;
; #pragma unroll
;         for (int s2 = 0; s2 < 16; ++s2) { if (s2 == ss) { mr = cr; mi = ci; } const float a = L8r * cr - L8i * ci + agg[s2 * 64 + nl], c = L8r * ci + L8i * cr + agg[s2 * 64 + 32 + nl]; cr = a; ci = c; }
.LBB0_818:
	v_add_u32_e32 v68, 0x400, v50
	v_add_u32_e32 v72, 0x8000, v2
	v_cndmask_b32_e64 v69, 0, v23, s[4:5]
	v_add_u32_e32 v76, 0x8400, v2
	v_add_u32_e32 v80, 0x8c00, v2
	s_add_i32 s61, s61, -1
	s_cmp_lg_u32 s61, 0
	ds_write_b128 v46, v[224:227]
	ds_write_b128 v47, v[228:231]
	ds_write_b128 v48, v[232:235]
	ds_write_b128 v49, v[236:239]
	v_lshl_add_u64 v[52:53], s[92:93], 0, v[12:13]
	global_load_dwordx4 v[224:227], v[52:53], off
	v_lshl_add_u64 v[52:53], s[92:93], 0, v[14:15]
	global_load_dwordx4 v[228:231], v[52:53], off
	v_lshl_add_u64 v[52:53], s[92:93], 0, v[16:17]
	global_load_dwordx4 v[232:235], v[52:53], off
	v_lshl_add_u64 v[52:53], s[92:93], 0, v[18:19]
	global_load_dwordx4 v[236:239], v[52:53], off
	v_lshl_add_u64 v[12:13], v[12:13], 0, s[44:45]
	v_lshl_add_u64 v[14:15], v[14:15], 0, s[44:45]
	v_lshl_add_u64 v[16:17], v[16:17], 0, s[44:45]
	v_lshl_add_u64 v[18:19], v[18:19], 0, s[44:45]
	s_waitcnt lgkmcnt(0)
	s_barrier
	ds_read2_b32 v[100:101], v50 offset1:32
	ds_read2_b32 v[102:103], v50 offset0:64 offset1:96
	ds_read2_b32 v[104:105], v50 offset0:128 offset1:160
	ds_read2_b32 v[106:107], v50 offset0:192 offset1:224
	ds_read2_b32 v[108:109], v68 offset1:32
	ds_read2_b32 v[110:111], v68 offset0:64 offset1:96
	ds_read2_b32 v[112:113], v68 offset0:128 offset1:160
	ds_read2_b32 v[114:115], v68 offset0:192 offset1:224
	s_waitcnt lgkmcnt(7)
	v_add_f32_e32 v59, v31, v100
	v_add_f32_e32 v57, v30, v101
	v_mul_f32_e32 v54, v29, v57
	v_fma_f32 v54, v0, v59, -v54
	s_waitcnt lgkmcnt(6)
	v_add_f32_e32 v58, v102, v54
	v_mul_f32_e32 v52, v0, v57
	v_fmac_f32_e32 v52, v29, v59
	v_add_f32_e32 v55, v103, v52
	v_mul_f32_e32 v54, v29, v55
	v_fma_f32 v54, v0, v58, -v54
	s_waitcnt lgkmcnt(5)
	v_add_f32_e32 v56, v104, v54
	v_mul_f32_e32 v52, v29, v58
	v_fmac_f32_e32 v52, v0, v55
	v_add_f32_e32 v53, v105, v52
	v_mul_f32_e32 v52, v29, v53
	v_fma_f32 v52, v0, v56, -v52
	s_waitcnt lgkmcnt(4)
	v_add_f32_e32 v54, v106, v52
	v_mul_f32_e32 v52, v29, v56
	v_fmac_f32_e32 v52, v0, v53
	v_add_f32_e32 v52, v107, v52
	v_mul_f32_e32 v62, v29, v52
	v_fma_f32 v62, v0, v54, -v62
	s_waitcnt lgkmcnt(3)
	v_add_f32_e32 v65, v108, v62
	v_mul_f32_e32 v60, v29, v54
	v_fmac_f32_e32 v60, v0, v52
	v_add_f32_e32 v63, v109, v60
	v_mul_f32_e32 v62, v29, v63
	v_fma_f32 v62, v0, v65, -v62
	s_waitcnt lgkmcnt(2)
	v_add_f32_e32 v64, v110, v62
	v_mul_f32_e32 v60, v29, v65
	v_fmac_f32_e32 v60, v0, v63
	v_add_f32_e32 v61, v111, v60
	v_mul_f32_e32 v60, v29, v61
	v_fma_f32 v60, v0, v64, -v60
	s_waitcnt lgkmcnt(1)
	v_add_f32_e32 v62, v112, v60
	v_mul_f32_e32 v60, v29, v64
	v_fmac_f32_e32 v60, v0, v61
	v_add_f32_e32 v60, v113, v60
	v_mul_f32_e32 v68, v29, v60
	v_fma_f32 v68, v0, v62, -v68
	s_waitcnt lgkmcnt(0)
	v_add_f32_e32 v66, v114, v68
	v_mul_f32_e32 v68, v29, v62
	v_fmac_f32_e32 v68, v0, v60
	v_add_f32_e32 v67, v115, v68
	ds_write2_b32 v51, v66, v67 offset1:32
	v_pk_mul_f32 v[66:67], v[4:5], v[22:23]
	s_waitcnt lgkmcnt(0)
	s_barrier
	v_sub_f32_e32 v70, v66, v67
	ds_read2_b32 v[66:67], v72 offset1:32
	v_cndmask_b32_e64 v68, 0, v22, s[4:5]
	v_pk_mul_f32 v[22:23], v[10:11], v[22:23]
	s_waitcnt lgkmcnt(0)
	v_add_f32_e32 v66, v70, v66
	v_add_f32_e32 v22, v22, v23
	v_add_f32_e32 v22, v22, v67
	v_cndmask_b32_e64 v74, v68, v66, s[6:7]
	v_cndmask_b32_e64 v75, v69, v22, s[6:7]
	ds_read2_b32 v[68:69], v72 offset0:64 offset1:96
	v_pk_mul_f32 v[22:23], v[10:11], v[22:23] op_sel_hi:[1,0]
	s_nop 0
	v_pk_fma_f32 v[70:71], v[4:5], v[66:67], v[22:23] neg_lo:[0,0,1] neg_hi:[0,0,1]
	v_pk_fma_f32 v[22:23], v[4:5], v[66:67], v[22:23] op_sel_hi:[1,0,1]
	s_nop 0
	v_mov_b32_e32 v71, v23
	ds_read2_b32 v[22:23], v72 offset0:128 offset1:160
	ds_read2_b32 v[66:67], v72 offset0:192 offset1:224
	s_waitcnt lgkmcnt(2)
	v_pk_add_f32 v[68:69], v[68:69], v[70:71]
	ds_read2_b32 v[72:73], v76 offset1:32
	v_pk_mul_f32 v[70:71], v[8:9], v[68:69]
	v_cndmask_b32_e64 v77, v74, v68, s[8:9]
	v_cndmask_b32_e64 v78, v75, v69, s[8:9]
	v_pk_fma_f32 v[74:75], v[6:7], v[68:69], v[70:71] op_sel:[0,0,1] op_sel_hi:[1,1,0] neg_lo:[0,0,1] neg_hi:[0,0,1]
	v_pk_fma_f32 v[68:69], v[6:7], v[68:69], v[70:71] op_sel:[0,0,1] op_sel_hi:[1,1,0]
	s_nop 0
	v_mov_b32_e32 v75, v69
	s_waitcnt lgkmcnt(2)
	v_pk_add_f32 v[22:23], v[22:23], v[74:75]
	s_nop 0
	v_pk_mul_f32 v[68:69], v[8:9], v[22:23]
	v_cndmask_b32_e64 v74, v77, v22, s[10:11]
	v_cndmask_b32_e64 v75, v78, v23, s[10:11]
	v_pk_fma_f32 v[70:71], v[6:7], v[22:23], v[68:69] op_sel:[0,0,1] op_sel_hi:[1,1,0] neg_lo:[0,0,1] neg_hi:[0,0,1]
	v_pk_fma_f32 v[22:23], v[6:7], v[22:23], v[68:69] op_sel:[0,0,1] op_sel_hi:[1,1,0]
	s_nop 0
	v_mov_b32_e32 v71, v23
	s_waitcnt lgkmcnt(1)
	v_pk_add_f32 v[22:23], v[66:67], v[70:71]
	s_nop 0
	v_pk_mul_f32 v[66:67], v[8:9], v[22:23]
	v_cndmask_b32_e64 v70, v74, v22, s[12:13]
	v_cndmask_b32_e64 v71, v75, v23, s[12:13]
	v_pk_fma_f32 v[68:69], v[6:7], v[22:23], v[66:67] op_sel:[0,0,1] op_sel_hi:[1,1,0] neg_lo:[0,0,1] neg_hi:[0,0,1]
	v_pk_fma_f32 v[22:23], v[6:7], v[22:23], v[66:67] op_sel:[0,0,1] op_sel_hi:[1,1,0]
	s_nop 0
	v_mov_b32_e32 v69, v23
	s_waitcnt lgkmcnt(0)
	v_pk_add_f32 v[22:23], v[72:73], v[68:69]
	ds_read2_b32 v[68:69], v76 offset0:64 offset1:96
	v_cndmask_b32_e64 v77, v70, v22, s[14:15]
	v_mul_f32_e32 v66, v5, v23
	v_mul_f32_e32 v70, v10, v22
	v_cndmask_b32_e64 v78, v71, v23, s[14:15]
	v_pk_fma_f32 v[66:67], v[4:5], v[22:23], v[66:67] op_sel_hi:[1,1,0] neg_lo:[0,0,1] neg_hi:[0,0,1]
	v_pk_fma_f32 v[22:23], v[10:11], v[22:23], v[70:71] op_sel_hi:[1,1,0]
	ds_read2_b32 v[70:71], v76 offset0:128 offset1:160
	ds_read2_b32 v[72:73], v76 offset0:192 offset1:224
	v_mov_b32_e32 v67, v23
	s_waitcnt lgkmcnt(2)
; __device__ __forceinline__ void s5_scan(const Prm& P, LAS unsigned char* lds, int item, int wave) {
;     ...
;         float cr = car, ci = cai, mr = 0.f, mi = 0.f;
; #pragma unroll
;         for (int s2 = 0; s2 < 16; ++s2) { if (s2 == ss) { mr = cr; mi = ci; } const float a = L8r * cr - L8i * ci + agg[s2 * 64 + nl], c = L8r * ci + L8i * cr + agg[s2 * 64 + 32 + nl]; cr = a; ci = c; }
;         car = cr; cai = ci;
	v_pk_add_f32 v[22:23], v[68:69], v[66:67]
	v_add_u32_e32 v76, 0x8800, v2
	v_pk_mul_f32 v[66:67], v[8:9], v[22:23]
	v_cndmask_b32_e64 v77, v77, v22, s[16:17]
	v_cndmask_b32_e64 v78, v78, v23, s[16:17]
	v_pk_fma_f32 v[68:69], v[6:7], v[22:23], v[66:67] op_sel:[0,0,1] op_sel_hi:[1,1,0] neg_lo:[0,0,1] neg_hi:[0,0,1]
	v_pk_fma_f32 v[22:23], v[6:7], v[22:23], v[66:67] op_sel:[0,0,1] op_sel_hi:[1,1,0]
	ds_read2_b32 v[74:75], v76 offset1:32
	v_mov_b32_e32 v69, v23
	s_waitcnt lgkmcnt(2)
	v_pk_add_f32 v[22:23], v[70:71], v[68:69]
	s_nop 0
	v_pk_mul_f32 v[66:67], v[8:9], v[22:23]
	v_cndmask_b32_e64 v70, v77, v22, s[18:19]
	v_cndmask_b32_e64 v71, v78, v23, s[18:19]
	v_pk_fma_f32 v[68:69], v[6:7], v[22:23], v[66:67] op_sel:[0,0,1] op_sel_hi:[1,1,0] neg_lo:[0,0,1] neg_hi:[0,0,1]
	v_pk_fma_f32 v[22:23], v[6:7], v[22:23], v[66:67] op_sel:[0,0,1] op_sel_hi:[1,1,0]
	s_nop 0
	v_mov_b32_e32 v69, v23
	s_waitcnt lgkmcnt(1)
	v_pk_add_f32 v[22:23], v[72:73], v[68:69]
	s_nop 0
	v_pk_mul_f32 v[66:67], v[8:9], v[22:23]
	v_cndmask_b32_e64 v70, v70, v22, s[20:21]
	v_cndmask_b32_e64 v71, v71, v23, s[20:21]
	v_pk_fma_f32 v[68:69], v[6:7], v[22:23], v[66:67] op_sel:[0,0,1] op_sel_hi:[1,1,0] neg_lo:[0,0,1] neg_hi:[0,0,1]
	v_pk_fma_f32 v[22:23], v[6:7], v[22:23], v[66:67] op_sel:[0,0,1] op_sel_hi:[1,1,0]
	s_nop 0
	v_mov_b32_e32 v69, v23
	s_waitcnt lgkmcnt(0)
	v_pk_add_f32 v[22:23], v[74:75], v[68:69]
	s_nop 0
	v_cndmask_b32_e64 v78, v70, v22, s[22:23]
	v_cndmask_b32_e64 v79, v71, v23, s[22:23]
	ds_read2_b32 v[66:67], v76 offset0:64 offset1:96
	ds_read2_b32 v[68:69], v76 offset0:128 offset1:160
	ds_read2_b32 v[70:71], v76 offset0:192 offset1:224
	v_pk_mul_f32 v[74:75], v[8:9], v[22:23]
	ds_read2_b32 v[72:73], v80 offset1:32
	v_pk_fma_f32 v[76:77], v[6:7], v[22:23], v[74:75] op_sel:[0,0,1] op_sel_hi:[1,1,0] neg_lo:[0,0,1] neg_hi:[0,0,1]
	v_pk_fma_f32 v[22:23], v[6:7], v[22:23], v[74:75] op_sel:[0,0,1] op_sel_hi:[1,1,0]
	s_nop 0
	v_mov_b32_e32 v77, v23
	s_waitcnt lgkmcnt(3)
	v_pk_add_f32 v[22:23], v[66:67], v[76:77]
	s_nop 0
	v_pk_mul_f32 v[66:67], v[8:9], v[22:23]
	v_cndmask_b32_e64 v76, v78, v22, s[24:25]
	v_cndmask_b32_e64 v77, v79, v23, s[24:25]
	v_pk_fma_f32 v[74:75], v[6:7], v[22:23], v[66:67] op_sel:[0,0,1] op_sel_hi:[1,1,0] neg_lo:[0,0,1] neg_hi:[0,0,1]
	v_pk_fma_f32 v[22:23], v[6:7], v[22:23], v[66:67] op_sel:[0,0,1] op_sel_hi:[1,1,0]
	s_nop 0
	v_mov_b32_e32 v75, v23
	s_waitcnt lgkmcnt(2)
	v_pk_add_f32 v[22:23], v[68:69], v[74:75]
	s_nop 0
	v_pk_mul_f32 v[66:67], v[8:9], v[22:23]
	v_cndmask_b32_e64 v74, v76, v22, s[26:27]
	v_cndmask_b32_e64 v75, v77, v23, s[26:27]
	v_pk_fma_f32 v[68:69], v[6:7], v[22:23], v[66:67] op_sel:[0,0,1] op_sel_hi:[1,1,0] neg_lo:[0,0,1] neg_hi:[0,0,1]
	v_pk_fma_f32 v[22:23], v[6:7], v[22:23], v[66:67] op_sel:[0,0,1] op_sel_hi:[1,1,0]
	s_nop 0
	v_mov_b32_e32 v69, v23
	s_waitcnt lgkmcnt(1)
	v_pk_add_f32 v[22:23], v[70:71], v[68:69]
	s_nop 0
	v_pk_mul_f32 v[66:67], v[8:9], v[22:23]
	v_cndmask_b32_e64 v76, v74, v22, s[28:29]
	v_cndmask_b32_e64 v77, v75, v23, s[28:29]
	v_pk_fma_f32 v[68:69], v[6:7], v[22:23], v[66:67] op_sel:[0,0,1] op_sel_hi:[1,1,0] neg_lo:[0,0,1] neg_hi:[0,0,1]
	v_pk_fma_f32 v[22:23], v[6:7], v[22:23], v[66:67] op_sel:[0,0,1] op_sel_hi:[1,1,0]
	v_lshl_add_u64 v[74:75], s[92:93], 0, v[20:21]
	v_mov_b32_e32 v69, v23
	s_waitcnt lgkmcnt(0)
	v_pk_add_f32 v[68:69], v[72:73], v[68:69]
	ds_read2_b32 v[22:23], v80 offset0:64 offset1:96
	ds_read2_b32 v[66:67], v80 offset0:128 offset1:160
	ds_read2_b32 v[70:71], v80 offset0:192 offset1:224
	v_pk_mul_f32 v[72:73], v[8:9], v[68:69]
	v_cndmask_b32_e64 v78, v76, v68, s[30:31]
	v_cndmask_b32_e64 v79, v77, v69, s[30:31]
	v_pk_fma_f32 v[76:77], v[6:7], v[68:69], v[72:73] op_sel:[0,0,1] op_sel_hi:[1,1,0] neg_lo:[0,0,1] neg_hi:[0,0,1]
	v_pk_fma_f32 v[68:69], v[6:7], v[68:69], v[72:73] op_sel:[0,0,1] op_sel_hi:[1,1,0]
	v_lshl_add_u64 v[20:21], v[20:21], 0, s[46:47]
	v_mov_b32_e32 v77, v69
	s_waitcnt lgkmcnt(2)
	v_pk_add_f32 v[22:23], v[22:23], v[76:77]
	s_nop 0
	v_pk_mul_f32 v[68:69], v[8:9], v[22:23]
	v_cndmask_b32_e64 v76, v78, v22, s[34:35]
	v_cndmask_b32_e64 v77, v79, v23, s[34:35]
	v_pk_fma_f32 v[72:73], v[6:7], v[22:23], v[68:69] op_sel:[0,0,1] op_sel_hi:[1,1,0] neg_lo:[0,0,1] neg_hi:[0,0,1]
	v_pk_fma_f32 v[22:23], v[6:7], v[22:23], v[68:69] op_sel:[0,0,1] op_sel_hi:[1,1,0]
	s_nop 0
	v_mov_b32_e32 v73, v23
	s_waitcnt lgkmcnt(1)
	v_pk_add_f32 v[22:23], v[66:67], v[72:73]
	s_nop 0
	v_pk_mul_f32 v[66:67], v[8:9], v[22:23]
	v_cndmask_b32_e32 v72, v76, v22, vcc
	v_cndmask_b32_e32 v73, v77, v23, vcc
	v_pk_fma_f32 v[68:69], v[6:7], v[22:23], v[66:67] op_sel:[0,0,1] op_sel_hi:[1,1,0] neg_lo:[0,0,1] neg_hi:[0,0,1]
	v_pk_fma_f32 v[22:23], v[6:7], v[22:23], v[66:67] op_sel:[0,0,1] op_sel_hi:[1,1,0]
	v_add_f32_e32 v66, 0, v73
	v_add_f32_e32 v22, 0, v72
	v_fmac_f32_e32 v22, 0x80000000, v73
	v_mov_b32_e32 v69, v23
	v_bfe_u32 v23, v22, 16, 1
	v_add3_u32 v67, v22, v23, s55
	v_add_co_u32_e64 v22, s[36:37], s58, v74
	v_fmac_f32_e32 v66, 0, v72
	s_nop 0
	v_addc_co_u32_e64 v23, s[36:37], 0, v75, s[36:37]
	s_waitcnt vmcnt(0)
; __device__ __forceinline__ unsigned f2bf(float f) { unsigned u = __builtin_bit_cast(unsigned, f); return (u + 0x7fffu + ((u >> 16) & 1u)) >> 16; }
; __device__ __forceinline__ void s5_scan(const Prm& P, LAS unsigned char* lds, int item, int wave) {
;     ...
;         float pwr = 1.f, pwi = 0.f;
; #pragma unroll
;         for (int j = 0; j < 8; ++j) { const float hr = xr[j] + pwr * mr - pwi * mi, hi = xi[j] + pwr * mi + pwi * mr;
;             bf16_t* dst = A5 + (rowbase + r0 + j) * 384 + 256 + n; dst[0] = (bf16_t)f2bf(hr); dst[64] = (bf16_t)f2bf(hi);
;             const float a = pwr * Lr - pwi * Li, c = pwr * Li + pwi * Lr; pwr = a; pwi = c; }
;         __syncthreads();
;     }
; __global__ void __launch_bounds__(NTHR, 2) fwd_megakernel(Prm P) {
;     ...
;         for (int it = bx; it < 256; it += G) hg_item<true>(P, lds, it, wave);
	global_store_short_d16_hi v[22:23], v67, off offset:512
	v_bfe_u32 v67, v66, 16, 1
	v_fmac_f32_e32 v59, v32, v72
	v_add3_u32 v66, v66, v67, s55
	v_fma_f32 v59, -v33, v73, v59
	global_store_short_d16_hi v[22:23], v66, off offset:640
	v_fmac_f32_e32 v57, v32, v73
	v_bfe_u32 v66, v59, 16, 1
	v_fmac_f32_e32 v57, v33, v72
	v_add3_u32 v59, v59, v66, s55
	global_store_short_d16_hi v[22:23], v59, off offset:1280
	v_bfe_u32 v59, v57, 16, 1
	v_add3_u32 v57, v57, v59, s55
	v_fmac_f32_e32 v58, v34, v72
	global_store_short_d16_hi v[22:23], v57, off offset:1408
	v_fma_f32 v57, -v35, v73, v58
	v_fmac_f32_e32 v55, v34, v73
	v_bfe_u32 v58, v57, 16, 1
	v_fmac_f32_e32 v55, v35, v72
	v_add3_u32 v57, v57, v58, s55
	global_store_short_d16_hi v[22:23], v57, off offset:2048
	v_bfe_u32 v57, v55, 16, 1
	v_add3_u32 v55, v55, v57, s55
	v_fmac_f32_e32 v56, v36, v72
	global_store_short_d16_hi v[22:23], v55, off offset:2176
	v_fma_f32 v55, -v37, v73, v56
	v_fmac_f32_e32 v53, v36, v73
	v_bfe_u32 v56, v55, 16, 1
	v_fmac_f32_e32 v53, v37, v72
	v_add3_u32 v55, v55, v56, s55
	global_store_short_d16_hi v[22:23], v55, off offset:2816
	v_bfe_u32 v55, v53, 16, 1
	v_add3_u32 v53, v53, v55, s55
	v_fmac_f32_e32 v54, v38, v72
	global_store_short_d16_hi v[22:23], v53, off offset:2944
	v_fma_f32 v53, -v39, v73, v54
	v_fmac_f32_e32 v52, v38, v73
	v_bfe_u32 v54, v53, 16, 1
	v_fmac_f32_e32 v52, v39, v72
	v_add3_u32 v53, v53, v54, s55
	global_store_short_d16_hi v[22:23], v53, off offset:3584
	v_bfe_u32 v53, v52, 16, 1
	v_add3_u32 v52, v52, v53, s55
	v_fmac_f32_e32 v65, v40, v72
	global_store_short_d16_hi v[22:23], v52, off offset:3712
	v_fma_f32 v22, -v41, v73, v65
	v_bfe_u32 v23, v22, 16, 1
	v_fmac_f32_e32 v63, v40, v73
	v_add3_u32 v52, v22, v23, s55
	v_add_co_u32_e64 v22, s[36:37], s59, v74
	v_fmac_f32_e32 v63, v41, v72
	s_nop 0
	v_addc_co_u32_e64 v23, s[36:37], 0, v75, s[36:37]
	global_store_short_d16_hi v[22:23], v52, off offset:256
	v_bfe_u32 v52, v63, 16, 1
	v_add3_u32 v52, v63, v52, s55
	v_fmac_f32_e32 v64, v42, v72
	global_store_short_d16_hi v[22:23], v52, off offset:384
	v_fma_f32 v52, -v43, v73, v64
	v_fmac_f32_e32 v61, v42, v73
	v_bfe_u32 v53, v52, 16, 1
	v_fmac_f32_e32 v61, v43, v72
	v_add3_u32 v52, v52, v53, s55
	global_store_short_d16_hi v[22:23], v52, off offset:1024
	v_bfe_u32 v52, v61, 16, 1
	v_add3_u32 v52, v61, v52, s55
	v_fmac_f32_e32 v62, v44, v72
	global_store_short_d16_hi v[22:23], v52, off offset:1152
	v_fma_f32 v52, -v45, v73, v62
	v_fmac_f32_e32 v60, v44, v73
	v_bfe_u32 v53, v52, 16, 1
	v_fmac_f32_e32 v60, v45, v72
	v_add3_u32 v52, v52, v53, s55
	global_store_short_d16_hi v[22:23], v52, off offset:1792
	v_bfe_u32 v52, v60, 16, 1
	v_add3_u32 v52, v60, v52, s55
	global_store_short_d16_hi v[22:23], v52, off offset:1920
	s_waitcnt lgkmcnt(0)
	v_pk_add_f32 v[22:23], v[70:71], v[68:69]
	s_barrier
	s_cbranch_scc1 .LBB0_818
	v_readlane_b32 s4, v255, 1
	s_add_i32 s60, s60, s4
	s_add_i32 s3, s3, s94
	s_add_i32 s2, s2, s33
	s_cmpk_gt_i32 s60, 0xff
	v_readlane_b32 s5, v255, 2
	s_cbranch_scc0 .LBB0_813
	v_writelane_b32 v255, s76, 20
	s_lshl_b32 s2, s97, 1
	s_add_u32 s62, s92, 0xf400000
	v_writelane_b32 v255, s77, 21
	v_writelane_b32 v255, s94, 22
	s_addc_u32 s63, s93, 0
	s_mov_b32 s75, 0
	v_writelane_b32 v255, s95, 23
	v_writelane_b32 v255, s90, 24
	s_mov_b32 s81, s75
	v_mbcnt_lo_u32_b32 v0, -1, 0
	v_writelane_b32 v255, s91, 25
	v_writelane_b32 v255, s2, 26
	s_lshr_b32 s2, s80, 7
	s_add_u32 s64, s92, 0x7400000
	s_addc_u32 s65, s93, 0
	s_add_u32 s66, s92, 0x13400000
	s_addc_u32 s67, s93, 0
	s_add_u32 s4, s92, 0x1c400000
	s_addc_u32 s5, s93, 0
	v_writelane_b32 v255, s4, 27
	s_lshl_b32 s3, s2, 5
	s_lshl_b32 s2, s2, 6
	v_writelane_b32 v255, s5, 28
	s_add_i32 s2, s2, 0
	v_writelane_b32 v255, s3, 29
	s_add_i32 s2, s2, 0x15c00
	v_writelane_b32 v255, s2, 30
	s_and_b32 s2, s80, 64
	v_writelane_b32 v255, s2, 31
	s_lshl_b32 s2, s97, 9
	s_add_i32 s60, s2, 0
	s_lshl_b32 s2, s97, 4
	s_add_i32 s61, s2, 0
	s_lshl_b32 s55, s97, 3
	s_add_i32 s60, s60, 0x20800
	s_add_i32 s58, s61, 0x11400
	s_cmpk_lt_u32 s80, 0xc0
	s_cselect_b64 s[76:77], -1, 0
	s_bfe_u32 s2, s80, 0x20006
	s_cmpk_gt_u32 s80, 0xff
	s_cselect_b64 s[4:5], -1, 0
	s_and_b32 s18, s80, 0xffffff80
	s_lshl_b32 s3, s2, 5
	s_lshl_b32 s2, s2, 7
	s_add_i32 s96, s18, 0
	s_and_b32 s59, s55, 0x1fffffe0
	v_writelane_b32 v255, s3, 32
	s_add_i32 s2, s2, 0
	s_add_i32 s96, s96, 0x21800
	v_writelane_b32 v255, s2, 33
	s_and_b64 s[2:3], s[88:89], exec
	s_mov_b32 s2, s97
	s_cselect_b32 s97, 0, 32
	s_cmp_eq_u32 s2, 2
	s_cselect_b32 s3, 32, 0
	s_cmpk_gt_u32 s80, 0x7f
	s_cselect_b64 s[6:7], -1, 0
	s_cmpk_gt_u32 s80, 0xbf
	s_cselect_b64 s[8:9], -1, 0
	s_cmpk_gt_u32 s80, 0x13f
	s_cselect_b64 s[10:11], -1, 0
	s_cmpk_gt_u32 s80, 0x17f
	s_cselect_b64 s[12:13], -1, 0
	s_cmpk_gt_u32 s80, 0x1bf
	v_writelane_b32 v255, s3, 34
	s_cselect_b64 s[14:15], -1, 0
	s_cmpk_gt_u32 s80, 0x1ff
	s_cselect_b64 s[16:17], -1, 0
	v_writelane_b32 v255, s2, 35
	s_or_b32 s3, s97, 1
	v_writelane_b32 v255, s3, 36
	s_or_b32 s3, s97, 2
	v_writelane_b32 v255, s3, 37
	s_or_b32 s3, s97, 3
	v_writelane_b32 v255, s3, 38
	s_or_b32 s3, s97, 8
	v_writelane_b32 v255, s3, 39
	s_or_b32 s3, s97, 9
	v_writelane_b32 v255, s3, 40
	s_or_b32 s3, s97, 10
	v_writelane_b32 v255, s3, 41
	s_or_b32 s3, s97, 11
	v_writelane_b32 v255, s3, 42
	s_or_b32 s3, s97, 16
	v_writelane_b32 v255, s3, 43
	s_or_b32 s3, s97, 17
	v_writelane_b32 v255, s3, 44
	s_or_b32 s3, s97, 18
	v_writelane_b32 v255, s3, 45
	s_or_b32 s3, s97, 19
	v_writelane_b32 v255, s3, 46
	s_or_b32 s3, s97, 24
	v_writelane_b32 v255, s3, 47
	s_or_b32 s3, s97, 25
	v_writelane_b32 v255, s3, 48
	s_or_b32 s3, s97, 26
	s_mulk_i32 s2, 0x880
	v_writelane_b32 v255, s3, 49
	s_or_b32 s3, s97, 27
	v_writelane_b32 v255, s3, 50
	s_add_i32 s2, s2, 0
	v_writelane_b32 v255, s2, 51
	s_add_u32 s2, s92, s18
	s_addc_u32 s3, s93, 0
	s_add_u32 s2, s2, 0x1f500040
	v_writelane_b32 v255, s2, 52
	s_addc_u32 s2, s3, 0
	v_writelane_b32 v255, s2, 53
	v_mov_b32_e32 v75, 0
	v_readlane_b32 s2, v255, 7
	v_readlane_b32 s3, v255, 8
	s_mov_b32 s20, s2
	s_lshl_b32 s54, s2, 4
	v_readlane_b32 s2, v255, 1
	s_lshl_b32 s2, s2, 4
	v_readlane_b32 s3, v255, 2
	v_writelane_b32 v255, s2, 54
	s_add_u32 s2, s55, 64
	v_writelane_b32 v255, s2, 55
	s_mov_b32 s2, s80
	v_writelane_b32 v255, s2, 56
	s_addc_u32 s90, 0, 0
	v_mbcnt_hi_u32_b32 v108, -1, v0
	v_writelane_b32 v255, s3, 57
	s_lshl_b64 s[2:3], s[80:81], 8
	s_and_b32 s2, s2, 0xffffc000
	s_add_u32 s18, s70, s2
	s_addc_u32 s19, s71, s3
	s_add_u32 s78, s18, 0x20000
	s_addc_u32 s79, s19, 0
	s_add_u32 s80, s92, s2
	s_addc_u32 s81, s93, s3
	s_movk_i32 s3, 0x110
	v_mov_b32_e32 v109, 0x358637bd
	s_movk_i32 s72, 0x90
	s_add_i32 s73, 0, 0x1e400
	s_movk_i32 s95, 0x7fff
	s_mov_b32 s2, s20
	s_mov_b32 s91, s20
	s_movk_i32 s94, 0x210
	s_branch .LBB0_822

; #define LAS __attribute__((address_space(3)))
; template <bool FULL, bool STORE = true>
; __device__ __forceinline__ void hg_item(const Prm& P, LAS unsigned char* lds, int item, int wave) {
;     ...
;             { const int tb = wave >> 2, vb = wave & 3; f32x16 o;
; #pragma unroll
;                 for (int r = 0; r < 16; ++r) o[r] = 0.f;
; #pragma unroll
;                 for (int ks = 0; ks < 4; ++ks) { if (ks < 2 || tb) { const bf16x8 a = *(const LAS bf16x8*)(lds + HL_PP + (tb * 32 + l31) * 144 + ks * 32 + lh * 16), bb = *(const LAS bf16x8*)(lds + HL_IVT + (vb * 32 + l31) * 144 + ks * 32 + lh * 16);
;                         o = __builtin_amdgcn_mfma_f32_32x32x16_bf16(a, bb, o, 0, 0, 0); } }
; #pragma unroll
;                 for (int ks = 0; ks < 8; ++ks) { const bf16x8 a = *(const LAS bf16x8*)(lds + HL_QD + (tb * 32 + l31) * 272 + ks * 32 + lh * 16), bb = *(const LAS bf16x8*)(lds + HL_ST + (vb * 32 + l31) * 272 + ks * 32 + lh * 16);
;                     o = __builtin_amdgcn_mfma_f32_32x32x16_bf16(a, bb, o, 0, 0, 0); }
; #pragma unroll
;                 for (int r = 0; r < 16; ++r) { const int t = tb * 32 + (r & 3) + 8 * (r >> 2) + 4 * lh; *(LAS float*)(lds + HL_OS + t * 528 + (vb * 32 + l31) * 4) = o[r]; }
;             }
;         }
; #pragma unroll
;         for (int g4 = 0; g4 < 4; ++g4) { const f32x4 d = *(const LAS f32x4*)(lds + HL_DC + (kb * 32 + 8 * g4 + 4 * lh) * 4);
; #pragma unroll
;             for (int i = 0; i < 2; ++i)
; #pragma unroll
;                 for (int j = 0; j < 4; ++j) S[i][4 * g4 + j] *= d[j]; }
; #pragma unroll
;         for (int ks = 0; ks < 4; ++ks) { const bf16x8 a = *(const LAS bf16x8*)(lds + HL_KDT + (kb * 32 + l31) * 144 + ks * 32 + lh * 16);
; #pragma unroll
;             for (int i = 0; i < 2; ++i) { const bf16x8 bb = *(const LAS bf16x8*)(lds + HL_IVT + ((vb0 + i) * 32 + l31) * 144 + ks * 32 + lh * 16); S[i] = __builtin_amdgcn_mfma_f32_32x32x16_bf16(a, bb, S[i], 0, 0, 0); } }
.LBB0_839:
	s_mov_b32 s33, 0x800000
	s_add_u32 s86, s86, 0x20000
	s_addc_u32 s87, s87, 0
	v_lshlrev_b32_e32 v104, 16, v52
	v_and_b32_e32 v105, 0xffff0000, v52
	v_lshlrev_b32_e32 v52, 16, v53
	v_and_b32_e32 v53, 0xffff0000, v53
	s_add_u32 s84, s84, 0x10000
	s_addc_u32 s85, s85, 0
	s_cmp_lg_u32 s86, 0x200000
	s_waitcnt lgkmcnt(6)
	v_mfma_f32_32x32x16_bf16 v[32:47], v[172:175], v[176:179], v[32:47]
	ds_read_b128 v[172:175], v151 offset:34944
	ds_read_b128 v[176:179], v152 offset:128
	s_waitcnt lgkmcnt(6)
	v_mfma_f32_32x32x16_bf16 v[32:47], v[180:183], v[184:187], v[32:47]
	ds_read_b128 v[180:183], v151 offset:34976
	ds_read_b128 v[184:187], v152 offset:160
	s_waitcnt lgkmcnt(6)
	v_mfma_f32_32x32x16_bf16 v[32:47], v[188:191], v[192:195], v[32:47]
	ds_read_b128 v[188:191], v151 offset:35008
	ds_read_b128 v[192:195], v152 offset:192
	s_waitcnt lgkmcnt(6)
	v_mfma_f32_32x32x16_bf16 v[32:47], v[196:199], v[200:203], v[32:47]
	ds_read_b128 v[196:199], v151 offset:35040
	ds_read_b128 v[200:203], v152 offset:224
	s_waitcnt lgkmcnt(6)
	v_mfma_f32_32x32x16_bf16 v[32:47], v[172:175], v[176:179], v[32:47]
	s_waitcnt lgkmcnt(4)
	v_mfma_f32_32x32x16_bf16 v[32:47], v[180:183], v[184:187], v[32:47]
	s_waitcnt lgkmcnt(2)
	v_mfma_f32_32x32x16_bf16 v[32:47], v[188:191], v[192:195], v[32:47]
	s_waitcnt lgkmcnt(0)
	v_mfma_f32_32x32x16_bf16 v[32:47], v[196:199], v[200:203], v[32:47]
	s_nop 11
	ds_write2_b32 v153, v32, v33 offset1:132
	v_add_u32_e32 v32, 0x400, v153
	ds_write2_b32 v32, v34, v35 offset0:8 offset1:140
	v_add_u32_e32 v32, 0x1000, v153
	ds_write2_b32 v32, v36, v37 offset0:32 offset1:164
	v_add_u32_e32 v32, 0x1400, v153
	ds_write2_b32 v32, v38, v39 offset0:40 offset1:172
	v_add_u32_e32 v32, 0x2000, v153
	ds_write2_b32 v32, v40, v41 offset0:64 offset1:196
	v_add_u32_e32 v32, 0x2400, v153
	ds_write2_b32 v32, v42, v43 offset0:72 offset1:204
	v_add_u32_e32 v32, 0x3000, v153
	ds_write2_b32 v32, v44, v45 offset0:96 offset1:228
	v_add_u32_e32 v32, 0x3400, v153
	ds_write2_b32 v32, v46, v47 offset0:104 offset1:236
	v_add_u32_e32 v220, s96, v128
	ds_read_b128 v[32:35], v220
	ds_read_b128 v[36:39], v220 offset:32
	ds_read_b128 v[40:43], v220 offset:64
	ds_read_b128 v[44:47], v220 offset:96
	ds_read_b128 v[172:175], v154 offset:52224
	ds_read_b128 v[188:191], v155
	ds_read_b128 v[204:207], v155 offset:4608
	ds_read_b128 v[176:179], v154 offset:52256
	ds_read_b128 v[192:195], v155 offset:32
	ds_read_b128 v[208:211], v155 offset:4640
	s_waitcnt lgkmcnt(9)
	v_pk_mul_f32 v[0:1], v[0:1], v[32:33]
	v_pk_mul_f32 v[2:3], v[2:3], v[34:35]
	v_pk_mul_f32 v[16:17], v[16:17], v[32:33]
	v_pk_mul_f32 v[18:19], v[18:19], v[34:35]
	s_waitcnt lgkmcnt(8)
	v_pk_mul_f32 v[4:5], v[4:5], v[36:37]
	v_pk_mul_f32 v[6:7], v[6:7], v[38:39]
	v_pk_mul_f32 v[20:21], v[20:21], v[36:37]
	v_pk_mul_f32 v[22:23], v[22:23], v[38:39]
	s_waitcnt lgkmcnt(7)
	v_pk_mul_f32 v[8:9], v[8:9], v[40:41]
	v_pk_mul_f32 v[10:11], v[10:11], v[42:43]
	v_pk_mul_f32 v[24:25], v[24:25], v[40:41]
	v_pk_mul_f32 v[26:27], v[26:27], v[42:43]
	s_waitcnt lgkmcnt(6)
	v_pk_mul_f32 v[12:13], v[12:13], v[44:45]
	v_pk_mul_f32 v[14:15], v[14:15], v[46:47]
	v_pk_mul_f32 v[28:29], v[28:29], v[44:45]
	v_pk_mul_f32 v[30:31], v[30:31], v[46:47]
	ds_read_b128 v[180:183], v154 offset:52288
	ds_read_b128 v[196:199], v155 offset:64
	ds_read_b128 v[212:215], v155 offset:4672
	ds_read_b128 v[184:187], v154 offset:52320
	ds_read_b128 v[200:203], v155 offset:96
	ds_read_b128 v[216:219], v155 offset:4704
	s_waitcnt vmcnt(18)
	v_cvt_f32_f16_e32 v78, v240
	v_cvt_f32_f16_sdwa v79, v240 dst_sel:DWORD dst_unused:UNUSED_PAD src0_sel:WORD_1
	v_cvt_f32_f16_e32 v80, v241
	v_cvt_f32_f16_sdwa v81, v241 dst_sel:DWORD dst_unused:UNUSED_PAD src0_sel:WORD_1
	v_cvt_f32_f16_e32 v82, v242
	v_cvt_f32_f16_sdwa v83, v242 dst_sel:DWORD dst_unused:UNUSED_PAD src0_sel:WORD_1
	v_cvt_f32_f16_e32 v84, v243
	v_cvt_f32_f16_sdwa v85, v243 dst_sel:DWORD dst_unused:UNUSED_PAD src0_sel:WORD_1
	v_cvt_f32_f16_e32 v86, v244
	v_cvt_f32_f16_sdwa v87, v244 dst_sel:DWORD dst_unused:UNUSED_PAD src0_sel:WORD_1
	v_cvt_f32_f16_e32 v88, v245
	v_cvt_f32_f16_sdwa v89, v245 dst_sel:DWORD dst_unused:UNUSED_PAD src0_sel:WORD_1
	v_cvt_f32_f16_e32 v90, v246
	v_cvt_f32_f16_sdwa v91, v246 dst_sel:DWORD dst_unused:UNUSED_PAD src0_sel:WORD_1
	v_cvt_f32_f16_e32 v92, v247
	v_cvt_f32_f16_sdwa v93, v247 dst_sel:DWORD dst_unused:UNUSED_PAD src0_sel:WORD_1
	s_nop 0
	v_pk_add_f32 v[32:33], v[78:79], 0 op_sel_hi:[1,0]
	v_pk_add_f32 v[32:33], v[32:33], v[80:81]
	v_pk_add_f32 v[32:33], v[32:33], v[82:83]
	v_pk_add_f32 v[32:33], v[32:33], v[84:85]
	v_pk_add_f32 v[32:33], v[32:33], v[86:87]
	v_pk_add_f32 v[32:33], v[32:33], v[88:89]
	v_pk_add_f32 v[32:33], v[32:33], v[90:91]
	v_pk_add_f32 v[32:33], v[32:33], v[92:93]
	v_add_u32_e32 v36, s60, v126
	ds_write_b64 v36, v[32:33]
	s_waitcnt lgkmcnt(0)
	s_barrier
; #define LAS __attribute__((address_space(3)))
; __device__ __forceinline__ unsigned pk2(float lo, float hi) { typedef float f2v __attribute__((ext_vector_type(2))); typedef __bf16 b2v __attribute__((ext_vector_type(2))); const f2v v = {lo, hi}; const b2v b = __builtin_convertvector(v, b2v); return __builtin_bit_cast(unsigned, b); }
; template <bool FULL, bool STORE = true>
; __device__ __forceinline__ void hg_item(const Prm& P, LAS unsigned char* lds, int item, int wave) {
;     ...
;         for (int ks = 0; ks < 4; ++ks) { const bf16x8 a = *(const LAS bf16x8*)(lds + HL_KDT + (kb * 32 + l31) * 144 + ks * 32 + lh * 16);
; #pragma unroll
;             for (int i = 0; i < 2; ++i) { const bf16x8 bb = *(const LAS bf16x8*)(lds + HL_IVT + ((vb0 + i) * 32 + l31) * 144 + ks * 32 + lh * 16); S[i] = __builtin_amdgcn_mfma_f32_32x32x16_bf16(a, bb, S[i], 0, 0, 0); } }
;         if (FULL) {
;             __syncthreads();
; #pragma unroll
;             for (int i = 0; i < 2; ++i)
; #pragma unroll
;                 for (int g4 = 0; g4 < 4; ++g4) { u32x2 w; w.x = pk2(S[i][4 * g4], S[i][4 * g4 + 1]); w.y = pk2(S[i][4 * g4 + 2], S[i][4 * g4 + 3]);
;                     *(LAS u32x2*)(lds + HL_ST + ((vb0 + i) * 32 + l31) * 272 + (kb * 32 + 8 * g4 + 4 * lh) * 2) = w; }
;             { const int t = tid >> 3, vs = (tid & 7) * 16; float o[16]; float ss = 0.f;
; #pragma unroll
;                 for (int q4 = 0; q4 < 4; ++q4) { const f32x4 x4 = *(const LAS f32x4*)(lds + HL_OS + t * 528 + (vs + 4 * q4) * 4);
; #pragma unroll
;                     for (int j = 0; j < 4; ++j) { o[4 * q4 + j] = x4[j]; ss += x4[j] * x4[j]; } }
;                 ss += __shfl_xor(ss, 1); ss += __shfl_xor(ss, 2); ss += __shfl_xor(ss, 4);
;                 const float r = rsqrtf(ss * (1.0f / 128.0f) + EPS);
;                 const size_t oo = (row0 + t) * 1024 + h * 128 + vs; const float* gn = P.in[I_HGNG] + h * 128 + vs;
;                 float g0[8], g1[8]; unpack8(gcur0, g0); unpack8(gcur1, g1);
;                 float w0[8], w1[8];
; #pragma unroll
;                 for (int j = 0; j < 8; ++j) { w0[j] = o[j] * r * gn[j] * g0[j]; w1[j] = o[8 + j] * r * gn[8 + j] * g1[j]; }
;                 if (STORE) { *(u32x4*)(AHG + oo) = pack8(w0); *(u32x4*)(AHG + oo + 8) = pack8(w1); }
;             }
	ds_read_b128 v[66:69], v157
	ds_read_b128 v[36:39], v157 offset:16
	ds_read_b128 v[44:47], v157 offset:32
	ds_read_b128 v[32:35], v157 offset:48
	s_waitcnt lgkmcnt(3)
	v_mul_f32_e32 v64, v67, v67
	v_mfma_f32_32x32x16_bf16 v[0:15], v[172:175], v[188:191], v[0:15]
	v_fmac_f32_e32 v64, v66, v66
	v_fmac_f32_e32 v64, v68, v68
	v_fmac_f32_e32 v64, v69, v69
	s_waitcnt lgkmcnt(2)
	v_fmac_f32_e32 v64, v36, v36
	v_fmac_f32_e32 v64, v37, v37
	v_fmac_f32_e32 v64, v38, v38
	v_fmac_f32_e32 v64, v39, v39
	v_mfma_f32_32x32x16_bf16 v[16:31], v[172:175], v[204:207], v[16:31]
	s_waitcnt lgkmcnt(1)
	v_pk_mul_f32 v[42:43], v[44:45], v[44:45]
	v_pk_mul_f32 v[40:41], v[46:47], v[46:47]
	v_add_f32_e32 v42, v42, v64
	v_add_f32_e32 v42, v43, v42
	v_add_f32_e32 v40, v40, v42
	v_add_f32_e32 v64, v41, v40
	s_waitcnt lgkmcnt(0)
	s_barrier
	v_pk_mul_f32 v[42:43], v[32:33], v[32:33]
	v_mfma_f32_32x32x16_bf16 v[0:15], v[176:179], v[192:195], v[0:15]
	v_pk_mul_f32 v[40:41], v[34:35], v[34:35]
	v_add_f32_e32 v42, v42, v64
	v_add_f32_e32 v42, v43, v42
	v_add_f32_e32 v40, v40, v42
	v_add_f32_e32 v40, v41, v40
	s_nop 1
	v_add_f32_dpp v40, v40, v40 quad_perm:[1,0,3,2] row_mask:0xf bank_mask:0xf
	s_nop 1
	v_add_f32_dpp v40, v40, v40 quad_perm:[2,3,0,1] row_mask:0xf bank_mask:0xf
	v_mfma_f32_32x32x16_bf16 v[16:31], v[176:179], v[208:211], v[16:31]
	s_nop 1
	v_add_f32_dpp v40, v40, v40 row_half_mirror row_mask:0xf bank_mask:0xf
	v_fmamk_f32 v40, v40, 0x3c000000, v109
	v_cmp_gt_f32_e32 vcc, s33, v40
	v_mul_f32_e32 v41, 0x4b800000, v40
	s_mov_b32 s33, 0x7400000
	v_cndmask_b32_e32 v40, v40, v41, vcc
	v_rsq_f32_e32 v40, v40
	s_nop 0
	v_mul_f32_e32 v41, 0x45800000, v40
	v_mfma_f32_32x32x16_bf16 v[0:15], v[180:183], v[196:199], v[0:15]
	v_cndmask_b32_e32 v74, v40, v41, vcc
	v_pk_mul_f32 v[106:107], v[66:67], v[74:75] op_sel_hi:[1,0]
	v_pk_mul_f32 v[46:47], v[46:47], v[74:75] op_sel_hi:[1,0]
	v_pk_mul_f32 v[36:37], v[36:37], v[74:75] op_sel_hi:[1,0]
	v_pk_mul_f32 v[32:33], v[32:33], v[74:75] op_sel_hi:[1,0]
	v_pk_mul_f32 v[44:45], v[44:45], v[74:75] op_sel_hi:[1,0]
	v_pk_mul_f32 v[38:39], v[38:39], v[74:75] op_sel_hi:[1,0]
	v_mfma_f32_32x32x16_bf16 v[16:31], v[180:183], v[212:215], v[16:31]
	v_pk_mul_f32 v[34:35], v[34:35], v[74:75] op_sel_hi:[1,0]
	s_waitcnt vmcnt(0)
	v_pk_mul_f32 v[32:33], v[224:225], v[32:33]
	v_pk_mul_f32 v[46:47], v[230:231], v[46:47]
	v_pk_mul_f32 v[36:37], v[232:233], v[36:37]
	v_pk_mul_f32 v[106:107], v[236:237], v[106:107]
	v_pk_mul_f32 v[44:45], v[228:229], v[44:45]
	v_pk_mul_f32 v[104:105], v[106:107], v[104:105]
	v_mfma_f32_32x32x16_bf16 v[0:15], v[184:187], v[200:203], v[0:15]
	v_lshlrev_b32_e32 v106, 16, v48
	v_and_b32_e32 v107, 0xffff0000, v48
	v_lshlrev_b32_e32 v48, 16, v49
	v_and_b32_e32 v49, 0xffff0000, v49
	v_pk_mul_f32 v[46:47], v[46:47], v[48:49]
	v_lshlrev_b32_e32 v48, 16, v54
	v_and_b32_e32 v49, 0xffff0000, v54
	v_mfma_f32_32x32x16_bf16 v[16:31], v[184:187], v[216:219], v[16:31]
	v_pk_mul_f32 v[36:37], v[36:37], v[48:49]
	v_lshlrev_b32_e32 v48, 16, v50
	v_and_b32_e32 v49, 0xffff0000, v50
	v_pk_mul_f32 v[64:65], v[68:69], v[74:75] op_sel_hi:[1,0]
	v_pk_mul_f32 v[40:41], v[32:33], v[48:49]
	v_lshlrev_b32_e32 v32, 16, v55
	v_and_b32_e32 v33, 0xffff0000, v55
	v_pk_mul_f32 v[38:39], v[234:235], v[38:39]
	v_pk_mul_f32 v[64:65], v[238:239], v[64:65]
	v_pk_mul_f32 v[38:39], v[38:39], v[32:33]
	v_lshlrev_b32_e32 v32, 16, v51
	v_and_b32_e32 v33, 0xffff0000, v51
	v_pk_mul_f32 v[34:35], v[226:227], v[34:35]
	v_pk_mul_f32 v[52:53], v[64:65], v[52:53]
	v_pk_mul_f32 v[42:43], v[34:35], v[32:33]
	v_cvt_pk_bf16_f32 v34, v36, v37
	v_add_co_u32_e32 v36, vcc, s33, v102
	v_pk_mul_f32 v[44:45], v[44:45], v[106:107]
	v_cvt_pk_bf16_f32 v32, v104, v105
	v_cvt_pk_bf16_f32 v33, v52, v53
	v_cvt_pk_bf16_f32 v35, v38, v39
	v_addc_co_u32_e32 v37, vcc, 0, v103, vcc
	v_mov_b64_e32 v[52:53], v[56:57]
	v_mov_b64_e32 v[48:49], v[60:61]
	global_store_dwordx4 v[36:37], v[32:35], off
	v_mov_b64_e32 v[54:55], v[58:59]
	v_mov_b64_e32 v[50:51], v[62:63]
	v_cvt_pk_bf16_f32 v32, v44, v45
	v_cvt_pk_bf16_f32 v33, v46, v47
	v_cvt_pk_bf16_f32 v34, v40, v41
	v_cvt_pk_bf16_f32 v35, v42, v43
	global_store_dwordx4 v[36:37], v[32:35], off offset:16
	s_nop 8
	v_cvt_pk_bf16_f32 v32, v0, v1
	v_cvt_pk_bf16_f32 v33, v2, v3
	v_cvt_pk_bf16_f32 v34, v4, v5
	v_cvt_pk_bf16_f32 v35, v6, v7
	ds_write2_b64 v156, v[32:33], v[34:35] offset1:2
	v_cvt_pk_bf16_f32 v32, v8, v9
	v_cvt_pk_bf16_f32 v33, v10, v11
	v_cvt_pk_bf16_f32 v34, v12, v13
	v_cvt_pk_bf16_f32 v35, v14, v15
	ds_write2_b64 v156, v[32:33], v[34:35] offset0:4 offset1:6
	v_cvt_pk_bf16_f32 v32, v16, v17
	v_cvt_pk_bf16_f32 v33, v18, v19
	v_cvt_pk_bf16_f32 v34, v20, v21
	v_cvt_pk_bf16_f32 v35, v22, v23
	v_add_u32_e32 v36, 0x2000, v156
	ds_write2_b64 v36, v[32:33], v[34:35] offset0:64 offset1:66
	v_cvt_pk_bf16_f32 v32, v24, v25
	v_cvt_pk_bf16_f32 v33, v26, v27
	v_cvt_pk_bf16_f32 v34, v28, v29
	v_cvt_pk_bf16_f32 v35, v30, v31
	ds_write2_b64 v36, v[32:33], v[34:35] offset0:68 offset1:70
	s_cbranch_scc0 .LBB0_821
